# tile-start LDS-DMA staging of epilogue constants (ssq rows, bias cols) per wave; kind-0 epilogue reads them from LDS instead of global loads behind the in-flight prefetch
# speedup vs baseline: 1.0004x; 1.0004x over previous
;     __device__ __forceinline__ void operator()(const f32x4 (&acc)[2][2][4][2], const Unit& u, int wr, int wc, int fr, int fq) const {
;     ...
;         for (int n = 0; n < 2; ++n) { const f32x4 x0 = *(const f32x4*)(cb + bcol0 + 4 * n), x1 = *(const f32x4*)(cb + bcol0 + HALF + 4 * n);
;             b0[2 * n] = (f32x2){x0[0], x0[1]}; b0[2 * n + 1] = (f32x2){x0[2], x0[3]}; b1[2 * n] = (f32x2){x1[0], x1[1]}; b1[2 * n + 1] = (f32x2){x1[2], x1[3]}; }
; #pragma unroll
;         for (int p = 0; p < 4; ++p) bz[p] = (MODE == 0 ? b0[p] : b1[p]) * NL2E;
;         float sq[2][4];
; #pragma unroll
;         for (int ai = 0; ai < 2; ++ai)
; #pragma unroll
;             for (int m = 0; m < 4; ++m) sq[ai][m] = ssq[row0 + ai * HALF + m * 16];
; template <class Epi, class Sched, bool ALIGN_EPI = false, bool SP2 = false>
; __device__ __forceinline__ void gemm_phase(PG8_LAS unsigned char* lds, const Gemm g, const Sched& S, const Epi& E) {
;     ...
;         for (int a = 0; a < 2; ++a)
; #pragma unroll
;             for (int b = 0; b < 2; ++b)
; #pragma unroll
;                 for (int m = 0; m < 4; ++m)
; #pragma unroll
;                     for (int n = 0; n < 2; ++n) acc[a][b][m][n] = (f32x4){0.f, 0.f, 0.f, 0.f};
;         cur = nxt; cA = nA; cB = nB; ++ui;
.LBB0_440:
	s_add_u32 s42, s60, 0x80
	s_addc_u32 s43, s61, 0
	s_add_u32 s17, s44, 0x100
	v_mov_b32_e32 v2, 0
	s_addc_u32 s60, s45, 0
	s_mov_b32 s44, 0
	s_cmp_gt_i32 s0, 2
	s_cbranch_scc1 .Lpf_skip
	s_lshr_b32 s100, s93, 10
	s_mul_i32 s100, s100, 0x900
	s_add_i32 s100, s100, 0x22000
	v_and_b32_e32 v231, 64, v1
	v_add_lshl_u32 v231, v231, v227, 2
	s_lshl_b32 s101, s14, 10
	s_add_u32 s64, s72, s101
	s_addc_u32 s65, s73, 0
	s_mov_b32 m0, s100
	s_nop 0
	global_load_lds_dword v231, s[64:65]
	s_add_i32 m0, s100, 0xffffff00
	s_nop 0
	global_load_lds_dword v231, s[64:65] offset:512
	s_cmp_gt_i32 s14, 63
	s_cselect_b32 s66, s56, s76
	s_cselect_b32 s67, s57, s77
	s_lshl_b32 s101, s15, 10
	s_add_u32 s66, s66, s101
	s_addc_u32 s67, s67, 0
	v_and_b32_e32 v240, 32, v227
	v_mul_u32_u24_e32 v240, 3, v240
	v_add_u32_e32 v240, v240, v227
	v_and_b32_e32 v241, 0x60, v229
	v_add_lshl_u32 v240, v240, v241, 2
	s_add_i32 m0, s100, 0x200
	s_nop 0
	global_load_lds_dword v240, s[66:67]
.Lpf_skip:
	v_mov_b32_e32 v3, v2
	v_mov_b32_e32 v4, v2
	v_mov_b32_e32 v5, v2
	v_mov_b32_e32 v10, v2
	v_mov_b32_e32 v11, v2
	v_mov_b32_e32 v12, v2
	v_mov_b32_e32 v13, v2
	v_mov_b32_e32 v18, v2
	v_mov_b32_e32 v19, v2
	v_mov_b32_e32 v20, v2
	v_mov_b32_e32 v21, v2
	v_mov_b32_e32 v26, v2
	v_mov_b32_e32 v27, v2
	v_mov_b32_e32 v28, v2
	v_mov_b32_e32 v29, v2
	v_mov_b32_e32 v34, v2
	v_mov_b32_e32 v35, v2
	v_mov_b32_e32 v36, v2
	v_mov_b32_e32 v37, v2
	v_mov_b32_e32 v42, v2
	v_mov_b32_e32 v43, v2
	v_mov_b32_e32 v44, v2
	v_mov_b32_e32 v45, v2
	v_mov_b32_e32 v50, v2
	v_mov_b32_e32 v51, v2
	v_mov_b32_e32 v52, v2
	v_mov_b32_e32 v53, v2
	v_mov_b32_e32 v58, v2
	v_mov_b32_e32 v59, v2
	v_mov_b32_e32 v60, v2
	v_mov_b32_e32 v61, v2
	v_mov_b32_e32 v6, v2
	v_mov_b32_e32 v7, v2
	v_mov_b32_e32 v8, v2
	v_mov_b32_e32 v9, v2
	v_mov_b32_e32 v14, v2
	v_mov_b32_e32 v15, v2
	v_mov_b32_e32 v16, v2
	v_mov_b32_e32 v17, v2
	v_mov_b32_e32 v22, v2
	v_mov_b32_e32 v23, v2
	v_mov_b32_e32 v24, v2
	v_mov_b32_e32 v25, v2
	v_mov_b32_e32 v30, v2
	v_mov_b32_e32 v31, v2
	v_mov_b32_e32 v32, v2
	v_mov_b32_e32 v33, v2
	v_mov_b32_e32 v38, v2
	v_mov_b32_e32 v39, v2
	v_mov_b32_e32 v40, v2
	v_mov_b32_e32 v41, v2
	v_mov_b32_e32 v46, v2
	v_mov_b32_e32 v47, v2
	v_mov_b32_e32 v48, v2
	v_mov_b32_e32 v49, v2
	v_mov_b32_e32 v54, v2
	v_mov_b32_e32 v55, v2
	v_mov_b32_e32 v56, v2
	v_mov_b32_e32 v57, v2
	v_mov_b32_e32 v62, v2
	v_mov_b32_e32 v63, v2
	v_mov_b32_e32 v64, v2
	v_mov_b32_e32 v65, v2
	v_mov_b32_e32 v66, v2
	v_mov_b32_e32 v67, v2
	v_mov_b32_e32 v68, v2
	v_mov_b32_e32 v69, v2
	v_mov_b32_e32 v74, v2
	v_mov_b32_e32 v75, v2
	v_mov_b32_e32 v76, v2
	v_mov_b32_e32 v77, v2
	v_mov_b32_e32 v82, v2
	v_mov_b32_e32 v83, v2
	v_mov_b32_e32 v84, v2
	v_mov_b32_e32 v85, v2
	v_mov_b32_e32 v90, v2
	v_mov_b32_e32 v91, v2
	v_mov_b32_e32 v92, v2
	v_mov_b32_e32 v93, v2
	v_mov_b32_e32 v98, v2
	v_mov_b32_e32 v99, v2
	v_mov_b32_e32 v100, v2
	v_mov_b32_e32 v101, v2
	v_mov_b32_e32 v106, v2
	v_mov_b32_e32 v107, v2
	v_mov_b32_e32 v108, v2
	v_mov_b32_e32 v109, v2
	v_mov_b32_e32 v114, v2
	v_mov_b32_e32 v115, v2
	v_mov_b32_e32 v116, v2
	v_mov_b32_e32 v117, v2
	v_mov_b32_e32 v118, v2
	v_mov_b32_e32 v119, v2
	v_mov_b32_e32 v120, v2
	v_mov_b32_e32 v121, v2
	v_mov_b32_e32 v70, v2
	v_mov_b32_e32 v71, v2
	v_mov_b32_e32 v72, v2
	v_mov_b32_e32 v73, v2
	v_mov_b32_e32 v78, v2
	v_mov_b32_e32 v79, v2
	v_mov_b32_e32 v80, v2
	v_mov_b32_e32 v81, v2
	v_mov_b32_e32 v86, v2
	v_mov_b32_e32 v87, v2
	v_mov_b32_e32 v88, v2
	v_mov_b32_e32 v89, v2
	v_mov_b32_e32 v94, v2
	v_mov_b32_e32 v95, v2
	v_mov_b32_e32 v96, v2
	v_mov_b32_e32 v97, v2
	v_mov_b32_e32 v102, v2
	v_mov_b32_e32 v103, v2
	v_mov_b32_e32 v104, v2
	v_mov_b32_e32 v105, v2
	v_mov_b32_e32 v110, v2
	v_mov_b32_e32 v111, v2
	v_mov_b32_e32 v112, v2
	v_mov_b32_e32 v113, v2
	v_mov_b32_e32 v122, v2
	v_mov_b32_e32 v123, v2
	v_mov_b32_e32 v124, v2
	v_mov_b32_e32 v125, v2
	v_mov_b32_e32 v126, v2
	v_mov_b32_e32 v127, v2
	v_mov_b32_e32 v128, v2
	v_mov_b32_e32 v129, v2

;     __device__ __forceinline__ void operator()(const f32x4 (&acc)[2][2][4][2], const Unit& u, int wr, int wc, int fr, int fq) const {
;         const float* cb = (u.pm >= 64) ? cb_ctx : cb_lat;
;         const int row0 = u.pm * BM + wr * 64 + fr, bcol0 = u.pn * BM + wc * 32 + 8 * fq, ocol = u.pn * HALF + wc * 32 + 8 * fq;
;         constexpr float NL2E = -1.44269504f;
;         f32x2 b0[4], b1[4], bz[4];
; #pragma unroll
;         for (int n = 0; n < 2; ++n) { const f32x4 x0 = *(const f32x4*)(cb + bcol0 + 4 * n), x1 = *(const f32x4*)(cb + bcol0 + HALF + 4 * n);
;             b0[2 * n] = (f32x2){x0[0], x0[1]}; b0[2 * n + 1] = (f32x2){x0[2], x0[3]}; b1[2 * n] = (f32x2){x1[0], x1[1]}; b1[2 * n + 1] = (f32x2){x1[2], x1[3]}; }
; #pragma unroll
;         for (int p = 0; p < 4; ++p) bz[p] = (MODE == 0 ? b0[p] : b1[p]) * NL2E;
;         float sq[2][4];
; #pragma unroll
;         for (int ai = 0; ai < 2; ++ai)
; #pragma unroll
;             for (int m = 0; m < 4; ++m) sq[ai][m] = ssq[row0 + ai * HALF + m * 16];
; #pragma unroll
;         for (int ai = 0; ai < 2; ++ai)
; #pragma unroll
;             for (int m = 0; m < 4; ++m) {
;                 const int row = row0 + ai * HALF + m * 16;
;                 const float rs = __builtin_amdgcn_rsqf(sq[ai][m] * (1.0f / 1024.0f) + RMS_EPS_F), rz = rs * NL2E;
;                 unsigned w[4];
; #pragma unroll
;                 for (int p = 0; p < 4; ++p) {
;                     const f32x4 a0 = acc[ai][0][m][p >> 1], a1 = acc[ai][1][m][p >> 1];
;                     const f32x2 c0 = (p & 1) ? (f32x2){a0[2], a0[3]} : (f32x2){a0[0], a0[1]}, c1 = (p & 1) ? (f32x2){a1[2], a1[3]} : (f32x2){a1[0], a1[1]};
;                     const f32x2 v0 = c0 * rs + b0[p], v1 = c1 * rs + b1[p];
;                     const f32x2 t = (MODE == 0 ? c0 : c1) * rz + bz[p];
;                     f32x2 d; d.x = __builtin_amdgcn_exp2f(t.x); d.y = __builtin_amdgcn_exp2f(t.y); d = d + 1.0f;
;                     f32x2 r; r.x = __builtin_amdgcn_rcpf(d.x); r.y = __builtin_amdgcn_rcpf(d.y);
;                     const f32x2 o = (MODE == 0) ? (v0 * v1) * r : v0 * r;
;                     w[p] = cvt_pk_bf16(o.x, o.y);
;                 }
;                 u32x4 wv; wv.x = w[0]; wv.y = w[1]; wv.z = w[2]; wv.w = w[3];
;                 *(u32x4*)(O + ((unsigned)row * (unsigned)ldc + (unsigned)ocol)) = wv;
.LBB0_507:
	s_cmp_eq_u32 s0, 1
	s_mov_b64 s[42:43], -1
	s_cbranch_scc1 .LBB0_509
	s_mov_b64 s[44:45], s[72:73]
	s_mov_b64 s[60:61], s[56:57]
	s_mov_b64 s[42:43], s[24:25]
	s_mov_b64 s[64:65], s[76:77]
	s_cmp_gt_i32 s14, 63
	s_cselect_b32 s17, s61, s65
	s_cselect_b32 s60, s60, s64
	v_lshl_or_b32 v132, s15, 8, v229
	v_lshl_add_u32 v158, s14, 8, v1
	v_mov_b32_e32 v130, s60
	v_mov_b32_e32 v131, s17
	v_ashrrev_i32_e32 v133, 31, v132
	v_ashrrev_i32_e32 v159, 31, v158
	v_lshl_add_u64 v[142:143], v[132:133], 2, v[130:131]
	v_lshl_add_u64 v[146:147], v[158:159], 2, s[44:45]
	s_lshr_b32 s100, s93, 10
	s_mul_i32 s100, s100, 0x900
	s_add_i32 s100, s100, 0x22000
	v_and_b32_e32 v175, 15, v1
	v_lshl_add_u32 v175, v175, 2, s100
	v_and_b32_e32 v176, 0x18, v229
	v_lshl_add_u32 v176, v176, 2, s100
	ds_read_b128 v[130:133], v176 offset:528
	ds_read_b128 v[138:141], v176 offset:512
	ds_read_b128 v[134:137], v176 offset:656
	s_nop 0
	ds_read_b128 v[142:145], v176 offset:640
	s_nop 0
	ds_read_b32 v148, v175
	ds_read_b32 v174, v175 offset:64
	ds_read_b32 v167, v175 offset:128
	ds_read_b32 v166, v175 offset:192
	ds_read_b32 v165, v175 offset:256
	ds_read_b32 v164, v175 offset:320
	ds_read_b32 v163, v175 offset:384
	ds_read_b32 v161, v175 offset:448
	v_lshl_or_b32 v160, s15, 7, v229
	s_mul_i32 s17, s90, 0x50
	s_waitcnt lgkmcnt(0)
	v_fmamk_f32 v146, v148, 0x3a800000, v213
	v_rsq_f32_e32 v162, v146
	v_pk_mul_f32 v[152:153], v[130:131], s[30:31] op_sel_hi:[1,0]
	v_pk_mul_f32 v[156:157], v[138:139], s[30:31] op_sel_hi:[1,0]
	v_mul_f32_e32 v168, 0xbfb8aa3b, v162
	v_pk_fma_f32 v[170:171], v[126:127], v[168:169], v[156:157] op_sel_hi:[1,0,1]
	v_pk_mul_f32 v[154:155], v[140:141], s[30:31] op_sel_hi:[1,0]
	v_exp_f32_e32 v170, v170
	v_exp_f32_e32 v171, v171
	v_pk_fma_f32 v[172:173], v[128:129], v[168:169], v[154:155] op_sel_hi:[1,0,1]
	v_pk_fma_f32 v[146:147], v[126:127], v[162:163], v[138:139] op_sel_hi:[1,0,1]
	v_exp_f32_e32 v172, v172
	v_exp_f32_e32 v173, v173
	v_pk_add_f32 v[170:171], v[170:171], 1.0 op_sel_hi:[1,0]
	v_pk_fma_f32 v[148:149], v[118:119], v[162:163], v[142:143] op_sel_hi:[1,0,1]
	v_rcp_f32_e32 v170, v170
	v_rcp_f32_e32 v171, v171
	v_pk_add_f32 v[172:173], v[172:173], 1.0 op_sel_hi:[1,0]
	v_pk_mul_f32 v[146:147], v[146:147], v[148:149]
	v_rcp_f32_e32 v172, v172
	v_rcp_f32_e32 v173, v173
	v_pk_mul_f32 v[146:147], v[146:147], v[170:171]
	v_pk_fma_f32 v[148:149], v[128:129], v[162:163], v[140:141] op_sel_hi:[1,0,1]
	v_pk_fma_f32 v[170:171], v[120:121], v[162:163], v[144:145] op_sel_hi:[1,0,1]
	v_pk_mul_f32 v[150:151], v[132:133], s[30:31] op_sel_hi:[1,0]
	v_pk_mul_f32 v[148:149], v[148:149], v[170:171]
	v_cvt_pk_bf16_f32 v146, v146, v147
	v_pk_fma_f32 v[170:171], v[114:115], v[162:163], v[134:135] op_sel_hi:[1,0,1]
	v_pk_mul_f32 v[148:149], v[148:149], v[172:173]
	v_pk_fma_f32 v[172:173], v[122:123], v[168:169], v[152:153] op_sel_hi:[1,0,1]
	v_pk_fma_f32 v[168:169], v[124:125], v[168:169], v[150:151] op_sel_hi:[1,0,1]
	v_exp_f32_e32 v172, v172
	v_exp_f32_e32 v173, v173
	v_exp_f32_e32 v168, v168
	v_exp_f32_e32 v169, v169
	v_cvt_pk_bf16_f32 v147, v148, v149
	v_pk_add_f32 v[172:173], v[172:173], 1.0 op_sel_hi:[1,0]
	v_pk_fma_f32 v[148:149], v[122:123], v[162:163], v[130:131] op_sel_hi:[1,0,1]
	v_rcp_f32_e32 v172, v172
	v_rcp_f32_e32 v173, v173
	v_pk_add_f32 v[168:169], v[168:169], 1.0 op_sel_hi:[1,0]
	v_pk_mul_f32 v[148:149], v[148:149], v[170:171]
	v_rcp_f32_e32 v168, v168
	v_rcp_f32_e32 v169, v169
	v_pk_mul_f32 v[148:149], v[148:149], v[172:173]
	v_pk_fma_f32 v[170:171], v[124:125], v[162:163], v[132:133] op_sel_hi:[1,0,1]
	v_pk_fma_f32 v[172:173], v[116:117], v[162:163], v[136:137] op_sel_hi:[1,0,1]
	v_mad_u64_u32 v[158:159], s[44:45], v158, s90, v[160:161]
	v_pk_mul_f32 v[170:171], v[170:171], v[172:173]
	v_mov_b32_e32 v159, v0
	v_pk_mul_f32 v[168:169], v[170:171], v[168:169]
	v_cvt_pk_bf16_f32 v148, v148, v149
	s_nop 0
	v_cvt_pk_bf16_f32 v149, v168, v169
	v_lshl_add_u64 v[168:169], v[158:159], 1, s[42:43]
	global_store_dwordx4 v[168:169], v[146:149], off
	v_add_u32_e32 v158, s12, v158
	s_nop 0
	v_fmamk_f32 v146, v174, 0x3a800000, v213
	v_rsq_f32_e32 v160, v146
	s_nop 0
	v_mul_f32_e32 v162, 0xbfb8aa3b, v160
	v_pk_fma_f32 v[168:169], v[110:111], v[162:163], v[156:157] op_sel_hi:[1,0,1]
	v_pk_fma_f32 v[170:171], v[112:113], v[162:163], v[154:155] op_sel_hi:[1,0,1]
	v_exp_f32_e32 v168, v168
	v_exp_f32_e32 v169, v169
	v_exp_f32_e32 v170, v170
	v_exp_f32_e32 v171, v171
	v_pk_fma_f32 v[146:147], v[110:111], v[160:161], v[138:139] op_sel_hi:[1,0,1]
	v_pk_add_f32 v[168:169], v[168:169], 1.0 op_sel_hi:[1,0]
	v_pk_fma_f32 v[148:149], v[106:107], v[160:161], v[142:143] op_sel_hi:[1,0,1]
	v_rcp_f32_e32 v168, v168
	v_rcp_f32_e32 v169, v169
	v_pk_add_f32 v[170:171], v[170:171], 1.0 op_sel_hi:[1,0]
	v_pk_mul_f32 v[146:147], v[146:147], v[148:149]
	v_rcp_f32_e32 v170, v170
	v_rcp_f32_e32 v171, v171
	v_pk_mul_f32 v[146:147], v[146:147], v[168:169]
	v_pk_fma_f32 v[148:149], v[112:113], v[160:161], v[140:141] op_sel_hi:[1,0,1]
	v_pk_fma_f32 v[168:169], v[108:109], v[160:161], v[144:145] op_sel_hi:[1,0,1]
	v_pk_fma_f32 v[172:173], v[104:105], v[162:163], v[150:151] op_sel_hi:[1,0,1]
	v_pk_mul_f32 v[148:149], v[148:149], v[168:169]
	v_exp_f32_e32 v172, v172
	v_pk_mul_f32 v[148:149], v[148:149], v[170:171]
	v_pk_fma_f32 v[170:171], v[102:103], v[162:163], v[152:153] op_sel_hi:[1,0,1]
	v_exp_f32_e32 v173, v173
	v_exp_f32_e32 v170, v170
	v_exp_f32_e32 v171, v171
	v_cvt_pk_bf16_f32 v146, v146, v147
	v_pk_add_f32 v[172:173], v[172:173], 1.0 op_sel_hi:[1,0]
	v_cvt_pk_bf16_f32 v147, v148, v149
	v_pk_add_f32 v[170:171], v[170:171], 1.0 op_sel_hi:[1,0]
; __device__ __forceinline__ unsigned cvt_pk_bf16(float lo, float hi) { unsigned r; asm volatile("v_cvt_pk_bf16_f32 %0, %1, %2" : "=v"(r) : "v"(lo), "v"(hi)); return r; }
;     __device__ __forceinline__ void operator()(const f32x4 (&acc)[2][2][4][2], const Unit& u, int wr, int wc, int fr, int fq) const {
;     ...
;             for (int m = 0; m < 4; ++m) {
;                 const int row = row0 + ai * HALF + m * 16;
;                 const float rs = __builtin_amdgcn_rsqf(sq[ai][m] * (1.0f / 1024.0f) + RMS_EPS_F), rz = rs * NL2E;
;                 unsigned w[4];
; #pragma unroll
;                 for (int p = 0; p < 4; ++p) {
;                     const f32x4 a0 = acc[ai][0][m][p >> 1], a1 = acc[ai][1][m][p >> 1];
;                     const f32x2 c0 = (p & 1) ? (f32x2){a0[2], a0[3]} : (f32x2){a0[0], a0[1]}, c1 = (p & 1) ? (f32x2){a1[2], a1[3]} : (f32x2){a1[0], a1[1]};
;                     const f32x2 v0 = c0 * rs + b0[p], v1 = c1 * rs + b1[p];
;                     const f32x2 t = (MODE == 0 ? c0 : c1) * rz + bz[p];
;                     f32x2 d; d.x = __builtin_amdgcn_exp2f(t.x); d.y = __builtin_amdgcn_exp2f(t.y); d = d + 1.0f;
;                     f32x2 r; r.x = __builtin_amdgcn_rcpf(d.x); r.y = __builtin_amdgcn_rcpf(d.y);
;                     const f32x2 o = (MODE == 0) ? (v0 * v1) * r : v0 * r;
;                     w[p] = cvt_pk_bf16(o.x, o.y);
;                 }
;                 u32x4 wv; wv.x = w[0]; wv.y = w[1]; wv.z = w[2]; wv.w = w[3];
;                 *(u32x4*)(O + ((unsigned)row * (unsigned)ldc + (unsigned)ocol)) = wv;
	v_pk_fma_f32 v[148:149], v[102:103], v[160:161], v[130:131] op_sel_hi:[1,0,1]
	v_rcp_f32_e32 v170, v170
	v_rcp_f32_e32 v171, v171
	v_pk_fma_f32 v[168:169], v[98:99], v[160:161], v[134:135] op_sel_hi:[1,0,1]
	v_rcp_f32_e32 v172, v172
	v_rcp_f32_e32 v173, v173
	v_pk_mul_f32 v[148:149], v[148:149], v[168:169]
	v_pk_fma_f32 v[168:169], v[104:105], v[160:161], v[132:133] op_sel_hi:[1,0,1]
	v_pk_mul_f32 v[148:149], v[148:149], v[170:171]
	v_pk_fma_f32 v[170:171], v[100:101], v[160:161], v[136:137] op_sel_hi:[1,0,1]
	v_cvt_pk_bf16_f32 v148, v148, v149
	s_nop 0
	v_pk_mul_f32 v[168:169], v[168:169], v[170:171]
	s_nop 0
	v_pk_mul_f32 v[168:169], v[168:169], v[172:173]
	s_nop 0
	v_cvt_pk_bf16_f32 v149, v168, v169
	v_lshl_add_u64 v[168:169], v[158:159], 1, s[42:43]
	global_store_dwordx4 v[168:169], v[146:149], off
	v_add_u32_e32 v158, s12, v158
	s_nop 0
	v_fmamk_f32 v146, v167, 0x3a800000, v213
	v_rsq_f32_e32 v160, v146
	s_nop 0
	v_mul_f32_e32 v162, 0xbfb8aa3b, v160
	v_pk_fma_f32 v[168:169], v[94:95], v[162:163], v[156:157] op_sel_hi:[1,0,1]
	v_pk_fma_f32 v[170:171], v[96:97], v[162:163], v[154:155] op_sel_hi:[1,0,1]
	v_exp_f32_e32 v168, v168
	v_exp_f32_e32 v169, v169
	v_exp_f32_e32 v170, v170
	v_exp_f32_e32 v171, v171
	v_pk_fma_f32 v[146:147], v[94:95], v[160:161], v[138:139] op_sel_hi:[1,0,1]
	v_pk_add_f32 v[168:169], v[168:169], 1.0 op_sel_hi:[1,0]
	v_pk_fma_f32 v[148:149], v[90:91], v[160:161], v[142:143] op_sel_hi:[1,0,1]
	v_rcp_f32_e32 v168, v168
	v_rcp_f32_e32 v169, v169
	v_pk_add_f32 v[170:171], v[170:171], 1.0 op_sel_hi:[1,0]
	v_pk_mul_f32 v[146:147], v[146:147], v[148:149]
	v_rcp_f32_e32 v170, v170
	v_rcp_f32_e32 v171, v171
	v_pk_mul_f32 v[146:147], v[146:147], v[168:169]
	v_pk_fma_f32 v[148:149], v[96:97], v[160:161], v[140:141] op_sel_hi:[1,0,1]
	v_pk_fma_f32 v[168:169], v[92:93], v[160:161], v[144:145] op_sel_hi:[1,0,1]
	v_pk_fma_f32 v[172:173], v[88:89], v[162:163], v[150:151] op_sel_hi:[1,0,1]
	v_pk_mul_f32 v[148:149], v[148:149], v[168:169]
	v_exp_f32_e32 v172, v172
	v_pk_mul_f32 v[148:149], v[148:149], v[170:171]
	v_pk_fma_f32 v[170:171], v[86:87], v[162:163], v[152:153] op_sel_hi:[1,0,1]
	v_exp_f32_e32 v173, v173
	v_exp_f32_e32 v170, v170
	v_exp_f32_e32 v171, v171
	v_cvt_pk_bf16_f32 v146, v146, v147
	v_pk_add_f32 v[172:173], v[172:173], 1.0 op_sel_hi:[1,0]
	v_cvt_pk_bf16_f32 v147, v148, v149
	v_pk_add_f32 v[170:171], v[170:171], 1.0 op_sel_hi:[1,0]
	v_pk_fma_f32 v[148:149], v[86:87], v[160:161], v[130:131] op_sel_hi:[1,0,1]
	v_rcp_f32_e32 v170, v170
	v_rcp_f32_e32 v171, v171
	v_pk_fma_f32 v[168:169], v[82:83], v[160:161], v[134:135] op_sel_hi:[1,0,1]
	v_rcp_f32_e32 v172, v172
	v_rcp_f32_e32 v173, v173
	v_pk_mul_f32 v[148:149], v[148:149], v[168:169]
	v_pk_fma_f32 v[168:169], v[88:89], v[160:161], v[132:133] op_sel_hi:[1,0,1]
	v_pk_mul_f32 v[148:149], v[148:149], v[170:171]
	v_pk_fma_f32 v[170:171], v[84:85], v[160:161], v[136:137] op_sel_hi:[1,0,1]
	v_cvt_pk_bf16_f32 v148, v148, v149
	s_nop 0
	v_pk_mul_f32 v[168:169], v[168:169], v[170:171]
	s_nop 0
	v_pk_mul_f32 v[168:169], v[168:169], v[172:173]
	s_nop 0
	v_cvt_pk_bf16_f32 v149, v168, v169
	v_lshl_add_u64 v[168:169], v[158:159], 1, s[42:43]
	global_store_dwordx4 v[168:169], v[146:149], off
	v_add_u32_e32 v158, s12, v158
	s_nop 0
	v_fmamk_f32 v146, v166, 0x3a800000, v213
	v_rsq_f32_e32 v160, v146
	s_nop 0
	v_mul_f32_e32 v162, 0xbfb8aa3b, v160
	v_pk_fma_f32 v[166:167], v[78:79], v[162:163], v[156:157] op_sel_hi:[1,0,1]
	v_pk_fma_f32 v[168:169], v[80:81], v[162:163], v[154:155] op_sel_hi:[1,0,1]
	v_exp_f32_e32 v166, v166
	v_exp_f32_e32 v167, v167
	v_exp_f32_e32 v168, v168
	v_exp_f32_e32 v169, v169
	v_pk_fma_f32 v[146:147], v[78:79], v[160:161], v[138:139] op_sel_hi:[1,0,1]
	v_pk_add_f32 v[166:167], v[166:167], 1.0 op_sel_hi:[1,0]
	v_pk_fma_f32 v[148:149], v[74:75], v[160:161], v[142:143] op_sel_hi:[1,0,1]
	v_rcp_f32_e32 v166, v166
	v_rcp_f32_e32 v167, v167
	v_pk_add_f32 v[168:169], v[168:169], 1.0 op_sel_hi:[1,0]
	v_pk_mul_f32 v[146:147], v[146:147], v[148:149]
	v_rcp_f32_e32 v168, v168
	v_rcp_f32_e32 v169, v169
	v_pk_mul_f32 v[146:147], v[146:147], v[166:167]
	v_pk_fma_f32 v[148:149], v[80:81], v[160:161], v[140:141] op_sel_hi:[1,0,1]
	v_pk_fma_f32 v[166:167], v[76:77], v[160:161], v[144:145] op_sel_hi:[1,0,1]
	v_pk_fma_f32 v[170:171], v[72:73], v[162:163], v[150:151] op_sel_hi:[1,0,1]
	v_pk_mul_f32 v[148:149], v[148:149], v[166:167]
	v_exp_f32_e32 v170, v170
	v_pk_mul_f32 v[148:149], v[148:149], v[168:169]
	v_pk_fma_f32 v[168:169], v[70:71], v[162:163], v[152:153] op_sel_hi:[1,0,1]
	v_exp_f32_e32 v171, v171
	v_exp_f32_e32 v168, v168
	v_exp_f32_e32 v169, v169
	v_cvt_pk_bf16_f32 v146, v146, v147
	v_pk_add_f32 v[170:171], v[170:171], 1.0 op_sel_hi:[1,0]
	v_cvt_pk_bf16_f32 v147, v148, v149
	v_pk_add_f32 v[168:169], v[168:169], 1.0 op_sel_hi:[1,0]
	v_pk_fma_f32 v[148:149], v[70:71], v[160:161], v[130:131] op_sel_hi:[1,0,1]
	v_rcp_f32_e32 v168, v168
	v_rcp_f32_e32 v169, v169
	v_pk_fma_f32 v[166:167], v[66:67], v[160:161], v[134:135] op_sel_hi:[1,0,1]
	v_rcp_f32_e32 v170, v170
	v_rcp_f32_e32 v171, v171
	v_pk_mul_f32 v[148:149], v[148:149], v[166:167]
	v_pk_fma_f32 v[166:167], v[72:73], v[160:161], v[132:133] op_sel_hi:[1,0,1]
	v_pk_mul_f32 v[148:149], v[148:149], v[168:169]
	v_pk_fma_f32 v[168:169], v[68:69], v[160:161], v[136:137] op_sel_hi:[1,0,1]
	v_cvt_pk_bf16_f32 v148, v148, v149
	s_nop 0
	v_pk_mul_f32 v[166:167], v[166:167], v[168:169]
	s_nop 0
	v_pk_mul_f32 v[166:167], v[166:167], v[170:171]
	s_nop 0
	v_cvt_pk_bf16_f32 v149, v166, v167
	v_lshl_add_u64 v[166:167], v[158:159], 1, s[42:43]
	global_store_dwordx4 v[166:167], v[146:149], off
	v_add_u32_e32 v158, s17, v158
	s_nop 0
; __device__ __forceinline__ unsigned cvt_pk_bf16(float lo, float hi) { unsigned r; asm volatile("v_cvt_pk_bf16_f32 %0, %1, %2" : "=v"(r) : "v"(lo), "v"(hi)); return r; }
;     __device__ __forceinline__ void operator()(const f32x4 (&acc)[2][2][4][2], const Unit& u, int wr, int wc, int fr, int fq) const {
;     ...
;             for (int m = 0; m < 4; ++m) {
;                 const int row = row0 + ai * HALF + m * 16;
;                 const float rs = __builtin_amdgcn_rsqf(sq[ai][m] * (1.0f / 1024.0f) + RMS_EPS_F), rz = rs * NL2E;
;                 unsigned w[4];
; #pragma unroll
;                 for (int p = 0; p < 4; ++p) {
;                     const f32x4 a0 = acc[ai][0][m][p >> 1], a1 = acc[ai][1][m][p >> 1];
;                     const f32x2 c0 = (p & 1) ? (f32x2){a0[2], a0[3]} : (f32x2){a0[0], a0[1]}, c1 = (p & 1) ? (f32x2){a1[2], a1[3]} : (f32x2){a1[0], a1[1]};
;                     const f32x2 v0 = c0 * rs + b0[p], v1 = c1 * rs + b1[p];
;                     const f32x2 t = (MODE == 0 ? c0 : c1) * rz + bz[p];
;                     f32x2 d; d.x = __builtin_amdgcn_exp2f(t.x); d.y = __builtin_amdgcn_exp2f(t.y); d = d + 1.0f;
;                     f32x2 r; r.x = __builtin_amdgcn_rcpf(d.x); r.y = __builtin_amdgcn_rcpf(d.y);
;                     const f32x2 o = (MODE == 0) ? (v0 * v1) * r : v0 * r;
;                     w[p] = cvt_pk_bf16(o.x, o.y);
;                 }
;                 u32x4 wv; wv.x = w[0]; wv.y = w[1]; wv.z = w[2]; wv.w = w[3];
;                 *(u32x4*)(O + ((unsigned)row * (unsigned)ldc + (unsigned)ocol)) = wv;
	v_fmamk_f32 v146, v165, 0x3a800000, v213
	v_rsq_f32_e32 v160, v146
	s_nop 0
	v_mul_f32_e32 v162, 0xbfb8aa3b, v160
	v_pk_fma_f32 v[166:167], v[62:63], v[162:163], v[156:157] op_sel_hi:[1,0,1]
	v_pk_fma_f32 v[168:169], v[64:65], v[162:163], v[154:155] op_sel_hi:[1,0,1]
	v_exp_f32_e32 v166, v166
	v_exp_f32_e32 v167, v167
	v_exp_f32_e32 v168, v168
	v_exp_f32_e32 v169, v169
	v_pk_fma_f32 v[146:147], v[62:63], v[160:161], v[138:139] op_sel_hi:[1,0,1]
	v_pk_add_f32 v[166:167], v[166:167], 1.0 op_sel_hi:[1,0]
	v_pk_fma_f32 v[148:149], v[58:59], v[160:161], v[142:143] op_sel_hi:[1,0,1]
	v_rcp_f32_e32 v166, v166
	v_rcp_f32_e32 v167, v167
	v_pk_add_f32 v[168:169], v[168:169], 1.0 op_sel_hi:[1,0]
	v_pk_mul_f32 v[146:147], v[146:147], v[148:149]
	v_rcp_f32_e32 v168, v168
	v_rcp_f32_e32 v169, v169
	v_pk_mul_f32 v[146:147], v[146:147], v[166:167]
	v_pk_fma_f32 v[148:149], v[64:65], v[160:161], v[140:141] op_sel_hi:[1,0,1]
	v_pk_fma_f32 v[166:167], v[60:61], v[160:161], v[144:145] op_sel_hi:[1,0,1]
	v_pk_fma_f32 v[170:171], v[56:57], v[162:163], v[150:151] op_sel_hi:[1,0,1]
	v_pk_mul_f32 v[148:149], v[148:149], v[166:167]
	v_exp_f32_e32 v170, v170
	v_pk_mul_f32 v[148:149], v[148:149], v[168:169]
	v_pk_fma_f32 v[168:169], v[54:55], v[162:163], v[152:153] op_sel_hi:[1,0,1]
	v_exp_f32_e32 v171, v171
	v_exp_f32_e32 v168, v168
	v_exp_f32_e32 v169, v169
	v_cvt_pk_bf16_f32 v146, v146, v147
	v_pk_add_f32 v[170:171], v[170:171], 1.0 op_sel_hi:[1,0]
	v_cvt_pk_bf16_f32 v147, v148, v149
	v_pk_add_f32 v[168:169], v[168:169], 1.0 op_sel_hi:[1,0]
	v_pk_fma_f32 v[148:149], v[54:55], v[160:161], v[130:131] op_sel_hi:[1,0,1]
	v_rcp_f32_e32 v168, v168
	v_rcp_f32_e32 v169, v169
	v_pk_fma_f32 v[166:167], v[50:51], v[160:161], v[134:135] op_sel_hi:[1,0,1]
	v_rcp_f32_e32 v170, v170
	v_rcp_f32_e32 v171, v171
	v_pk_mul_f32 v[148:149], v[148:149], v[166:167]
	v_pk_fma_f32 v[166:167], v[56:57], v[160:161], v[132:133] op_sel_hi:[1,0,1]
	v_pk_mul_f32 v[148:149], v[148:149], v[168:169]
	v_pk_fma_f32 v[168:169], v[52:53], v[160:161], v[136:137] op_sel_hi:[1,0,1]
	v_cvt_pk_bf16_f32 v148, v148, v149
	s_nop 0
	v_pk_mul_f32 v[166:167], v[166:167], v[168:169]
	s_nop 0
	v_pk_mul_f32 v[166:167], v[166:167], v[170:171]
	s_nop 0
	v_cvt_pk_bf16_f32 v149, v166, v167
	v_lshl_add_u64 v[166:167], v[158:159], 1, s[42:43]
	global_store_dwordx4 v[166:167], v[146:149], off
	v_add_u32_e32 v158, s12, v158
	s_nop 0
	v_fmamk_f32 v146, v164, 0x3a800000, v213
	v_rsq_f32_e32 v160, v146
	s_nop 0
	v_mul_f32_e32 v162, 0xbfb8aa3b, v160
	v_pk_fma_f32 v[164:165], v[46:47], v[162:163], v[156:157] op_sel_hi:[1,0,1]
	v_pk_fma_f32 v[166:167], v[48:49], v[162:163], v[154:155] op_sel_hi:[1,0,1]
	v_exp_f32_e32 v164, v164
	v_exp_f32_e32 v165, v165
	v_exp_f32_e32 v166, v166
	v_exp_f32_e32 v167, v167
	v_pk_fma_f32 v[146:147], v[46:47], v[160:161], v[138:139] op_sel_hi:[1,0,1]
	v_pk_add_f32 v[164:165], v[164:165], 1.0 op_sel_hi:[1,0]
	v_pk_fma_f32 v[148:149], v[42:43], v[160:161], v[142:143] op_sel_hi:[1,0,1]
	v_rcp_f32_e32 v164, v164
	v_rcp_f32_e32 v165, v165
	v_pk_add_f32 v[166:167], v[166:167], 1.0 op_sel_hi:[1,0]
	v_pk_mul_f32 v[146:147], v[146:147], v[148:149]
	v_rcp_f32_e32 v166, v166
	v_rcp_f32_e32 v167, v167
	v_pk_mul_f32 v[146:147], v[146:147], v[164:165]
	v_pk_fma_f32 v[148:149], v[48:49], v[160:161], v[140:141] op_sel_hi:[1,0,1]
	v_pk_fma_f32 v[164:165], v[44:45], v[160:161], v[144:145] op_sel_hi:[1,0,1]
	v_pk_fma_f32 v[168:169], v[40:41], v[162:163], v[150:151] op_sel_hi:[1,0,1]
	v_pk_mul_f32 v[148:149], v[148:149], v[164:165]
	v_exp_f32_e32 v168, v168
	v_pk_mul_f32 v[148:149], v[148:149], v[166:167]
	v_pk_fma_f32 v[166:167], v[38:39], v[162:163], v[152:153] op_sel_hi:[1,0,1]
	v_exp_f32_e32 v169, v169
	v_exp_f32_e32 v166, v166
	v_exp_f32_e32 v167, v167
	v_cvt_pk_bf16_f32 v146, v146, v147
	v_pk_add_f32 v[168:169], v[168:169], 1.0 op_sel_hi:[1,0]
	v_cvt_pk_bf16_f32 v147, v148, v149
	v_pk_add_f32 v[166:167], v[166:167], 1.0 op_sel_hi:[1,0]
	v_pk_fma_f32 v[148:149], v[38:39], v[160:161], v[130:131] op_sel_hi:[1,0,1]
	v_rcp_f32_e32 v166, v166
	v_rcp_f32_e32 v167, v167
	v_pk_fma_f32 v[164:165], v[34:35], v[160:161], v[134:135] op_sel_hi:[1,0,1]
	v_rcp_f32_e32 v168, v168
	v_rcp_f32_e32 v169, v169
	v_pk_mul_f32 v[148:149], v[148:149], v[164:165]
	v_pk_fma_f32 v[164:165], v[40:41], v[160:161], v[132:133] op_sel_hi:[1,0,1]
	v_pk_mul_f32 v[148:149], v[148:149], v[166:167]
	v_pk_fma_f32 v[166:167], v[36:37], v[160:161], v[136:137] op_sel_hi:[1,0,1]
	v_cvt_pk_bf16_f32 v148, v148, v149
	s_nop 0
	v_pk_mul_f32 v[164:165], v[164:165], v[166:167]
	s_nop 0
	v_pk_mul_f32 v[164:165], v[164:165], v[168:169]
	s_nop 0
	v_cvt_pk_bf16_f32 v149, v164, v165
	v_lshl_add_u64 v[164:165], v[158:159], 1, s[42:43]
	global_store_dwordx4 v[164:165], v[146:149], off
	v_add_u32_e32 v158, s12, v158
	s_nop 0
; __device__ __forceinline__ unsigned cvt_pk_bf16(float lo, float hi) { unsigned r; asm volatile("v_cvt_pk_bf16_f32 %0, %1, %2" : "=v"(r) : "v"(lo), "v"(hi)); return r; }
;     __device__ __forceinline__ void operator()(const f32x4 (&acc)[2][2][4][2], const Unit& u, int wr, int wc, int fr, int fq) const {
;     ...
;             for (int m = 0; m < 4; ++m) {
;                 const int row = row0 + ai * HALF + m * 16;
;                 const float rs = __builtin_amdgcn_rsqf(sq[ai][m] * (1.0f / 1024.0f) + RMS_EPS_F), rz = rs * NL2E;
;                 unsigned w[4];
; #pragma unroll
;                 for (int p = 0; p < 4; ++p) {
;                     const f32x4 a0 = acc[ai][0][m][p >> 1], a1 = acc[ai][1][m][p >> 1];
;                     const f32x2 c0 = (p & 1) ? (f32x2){a0[2], a0[3]} : (f32x2){a0[0], a0[1]}, c1 = (p & 1) ? (f32x2){a1[2], a1[3]} : (f32x2){a1[0], a1[1]};
;                     const f32x2 v0 = c0 * rs + b0[p], v1 = c1 * rs + b1[p];
;                     const f32x2 t = (MODE == 0 ? c0 : c1) * rz + bz[p];
;                     f32x2 d; d.x = __builtin_amdgcn_exp2f(t.x); d.y = __builtin_amdgcn_exp2f(t.y); d = d + 1.0f;
;                     f32x2 r; r.x = __builtin_amdgcn_rcpf(d.x); r.y = __builtin_amdgcn_rcpf(d.y);
;                     const f32x2 o = (MODE == 0) ? (v0 * v1) * r : v0 * r;
;                     w[p] = cvt_pk_bf16(o.x, o.y);
;                 }
;                 u32x4 wv; wv.x = w[0]; wv.y = w[1]; wv.z = w[2]; wv.w = w[3];
;                 *(u32x4*)(O + ((unsigned)row * (unsigned)ldc + (unsigned)ocol)) = wv;
	v_fmamk_f32 v146, v163, 0x3a800000, v213
	v_rsq_f32_e32 v160, v146
	s_nop 0
	v_mul_f32_e32 v162, 0xbfb8aa3b, v160
	v_pk_fma_f32 v[164:165], v[30:31], v[162:163], v[156:157] op_sel_hi:[1,0,1]
	v_pk_fma_f32 v[166:167], v[32:33], v[162:163], v[154:155] op_sel_hi:[1,0,1]
	v_exp_f32_e32 v164, v164
	v_exp_f32_e32 v165, v165
	v_exp_f32_e32 v166, v166
	v_exp_f32_e32 v167, v167
	v_pk_fma_f32 v[146:147], v[30:31], v[160:161], v[138:139] op_sel_hi:[1,0,1]
	v_pk_add_f32 v[164:165], v[164:165], 1.0 op_sel_hi:[1,0]
	v_pk_fma_f32 v[148:149], v[26:27], v[160:161], v[142:143] op_sel_hi:[1,0,1]
	v_rcp_f32_e32 v164, v164
	v_rcp_f32_e32 v165, v165
	v_pk_add_f32 v[166:167], v[166:167], 1.0 op_sel_hi:[1,0]
	v_pk_mul_f32 v[146:147], v[146:147], v[148:149]
	v_rcp_f32_e32 v166, v166
	v_rcp_f32_e32 v167, v167
	v_pk_mul_f32 v[146:147], v[146:147], v[164:165]
	v_pk_fma_f32 v[148:149], v[32:33], v[160:161], v[140:141] op_sel_hi:[1,0,1]
	v_pk_fma_f32 v[164:165], v[28:29], v[160:161], v[144:145] op_sel_hi:[1,0,1]
	v_cvt_pk_bf16_f32 v146, v146, v147
	s_nop 0
	v_pk_mul_f32 v[148:149], v[148:149], v[164:165]
	v_pk_fma_f32 v[164:165], v[18:19], v[160:161], v[134:135] op_sel_hi:[1,0,1]
	v_pk_mul_f32 v[148:149], v[148:149], v[166:167]
	v_pk_fma_f32 v[166:167], v[22:23], v[162:163], v[152:153] op_sel_hi:[1,0,1]
	v_pk_fma_f32 v[162:163], v[24:25], v[162:163], v[150:151] op_sel_hi:[1,0,1]
	v_exp_f32_e32 v166, v166
	v_exp_f32_e32 v167, v167
	v_exp_f32_e32 v162, v162
	v_exp_f32_e32 v163, v163
	v_cvt_pk_bf16_f32 v147, v148, v149
	v_pk_add_f32 v[166:167], v[166:167], 1.0 op_sel_hi:[1,0]
	v_pk_fma_f32 v[148:149], v[22:23], v[160:161], v[130:131] op_sel_hi:[1,0,1]
	v_rcp_f32_e32 v166, v166
	v_rcp_f32_e32 v167, v167
	v_pk_add_f32 v[162:163], v[162:163], 1.0 op_sel_hi:[1,0]
	v_pk_mul_f32 v[148:149], v[148:149], v[164:165]
	v_rcp_f32_e32 v162, v162
	v_rcp_f32_e32 v163, v163
	v_pk_mul_f32 v[148:149], v[148:149], v[166:167]
	v_pk_fma_f32 v[164:165], v[24:25], v[160:161], v[132:133] op_sel_hi:[1,0,1]
	v_pk_fma_f32 v[166:167], v[20:21], v[160:161], v[136:137] op_sel_hi:[1,0,1]
	v_cvt_pk_bf16_f32 v148, v148, v149
	s_nop 0
	v_pk_mul_f32 v[164:165], v[164:165], v[166:167]
	s_nop 0
	v_pk_mul_f32 v[162:163], v[164:165], v[162:163]
	s_nop 0
	v_cvt_pk_bf16_f32 v149, v162, v163
	v_lshl_add_u64 v[162:163], v[158:159], 1, s[42:43]
	global_store_dwordx4 v[162:163], v[146:149], off
	s_nop 1
	v_fmamk_f32 v146, v161, 0x3a800000, v213
	v_rsq_f32_e32 v146, v146
	s_nop 0
	v_mul_f32_e32 v148, 0xbfb8aa3b, v146
	v_pk_fma_f32 v[138:139], v[14:15], v[146:147], v[138:139] op_sel_hi:[1,0,1]
	v_pk_fma_f32 v[142:143], v[10:11], v[146:147], v[142:143] op_sel_hi:[1,0,1]
	v_pk_fma_f32 v[156:157], v[14:15], v[148:149], v[156:157] op_sel_hi:[1,0,1]
	v_pk_mul_f32 v[138:139], v[138:139], v[142:143]
	v_pk_fma_f32 v[142:143], v[12:13], v[146:147], v[144:145] op_sel_hi:[1,0,1]
	v_pk_fma_f32 v[144:145], v[16:17], v[148:149], v[154:155] op_sel_hi:[1,0,1]
	v_exp_f32_e32 v156, v156
	v_exp_f32_e32 v157, v157
	v_exp_f32_e32 v144, v144
	v_exp_f32_e32 v145, v145
	v_pk_fma_f32 v[140:141], v[16:17], v[146:147], v[140:141] op_sel_hi:[1,0,1]
	v_pk_add_f32 v[156:157], v[156:157], 1.0 op_sel_hi:[1,0]
	v_pk_mul_f32 v[140:141], v[140:141], v[142:143]
	v_pk_add_f32 v[144:145], v[144:145], 1.0 op_sel_hi:[1,0]
	v_rcp_f32_e32 v156, v156
	v_rcp_f32_e32 v157, v157
	v_rcp_f32_e32 v144, v144
	v_rcp_f32_e32 v145, v145
	v_pk_fma_f32 v[130:131], v[6:7], v[146:147], v[130:131] op_sel_hi:[1,0,1]
	v_pk_mul_f32 v[138:139], v[138:139], v[156:157]
	v_pk_fma_f32 v[134:135], v[2:3], v[146:147], v[134:135] op_sel_hi:[1,0,1]
	v_pk_mul_f32 v[140:141], v[140:141], v[144:145]
	v_cvt_pk_bf16_f32 v138, v138, v139
	v_pk_mul_f32 v[130:131], v[130:131], v[134:135]
	v_cvt_pk_bf16_f32 v139, v140, v141
	v_pk_fma_f32 v[140:141], v[6:7], v[148:149], v[152:153] op_sel_hi:[1,0,1]
	v_pk_fma_f32 v[134:135], v[8:9], v[148:149], v[150:151] op_sel_hi:[1,0,1]
	v_exp_f32_e32 v140, v140
	v_exp_f32_e32 v141, v141
	v_exp_f32_e32 v134, v134
	v_exp_f32_e32 v135, v135
	v_pk_add_f32 v[140:141], v[140:141], 1.0 op_sel_hi:[1,0]
	s_nop 0
	v_rcp_f32_e32 v140, v140
	v_rcp_f32_e32 v141, v141
	v_pk_add_f32 v[134:135], v[134:135], 1.0 op_sel_hi:[1,0]
	v_pk_mul_f32 v[130:131], v[130:131], v[140:141]
	v_rcp_f32_e32 v134, v134
	v_rcp_f32_e32 v135, v135
	v_cvt_pk_bf16_f32 v140, v130, v131
	v_pk_fma_f32 v[130:131], v[8:9], v[146:147], v[132:133] op_sel_hi:[1,0,1]
	v_pk_fma_f32 v[132:133], v[4:5], v[146:147], v[136:137] op_sel_hi:[1,0,1]
	s_nop 0
	v_pk_mul_f32 v[130:131], v[130:131], v[132:133]
	s_nop 0
	v_pk_mul_f32 v[130:131], v[130:131], v[134:135]
	s_nop 0
	v_cvt_pk_bf16_f32 v141, v130, v131
	v_add_u32_e32 v130, s12, v158
	v_mov_b32_e32 v131, v0
	v_lshl_add_u64 v[130:131], v[130:131], 1, s[42:43]
	s_mov_b64 s[42:43], 0
	global_store_dwordx4 v[130:131], v[138:141], off
